# ACT stored block-tiled [M/256][K/64][256][64]: SwiGLU epilogue store addresses + GROWS_FFN A-operand addressing (DRAM-page-friendly 32KB K-step blocks)
# baseline (speedup 1.0000x reference)
; #define GAS __attribute__((address_space(1)))
; #define PG8_LAS __attribute__((address_space(3)))
; template <class Epi, class Sched, bool ALIGN_EPI = false, bool SP2 = false>
; __device__ __forceinline__ void gemm_phase(PG8_LAS unsigned char* lds, const Gemm g, const Sched& S, const Epi& E, const int tid) {
;     const int wid = __builtin_amdgcn_readfirstlane(tid >> 6), lane = tid & 63, wr = wid >> 2, wc = wid & 3, fr = lane & 15, fq = lane >> 4;
;     const int K = g.K, nt = (g.Kloop ? g.Kloop : g.K) / BK;
;     unsigned voffA[2], voffB[2];
; #pragma unroll
;     for (int i = 0; i < 2; ++i) { int R, C; stage_rc(tid * 16 + i * 8192, R, C); const int Rb = Epi::PERM ? ((R & ~31) + perm32(R & 31)) : R;
;         voffA[i] = (unsigned)(R * K + C) * 2u; voffB[i] = (unsigned)(Rb * K + C) * 2u; }
;     const size_t kstep = (size_t)(BK * 2);
;     const size_t hstep = (size_t)HALF * K * 2;
;     const size_t tstep = 2 * hstep;
;     const unsigned ldsw = (unsigned)wid * 1024u;
;     const int aoff = lds_byte(wr * 64 + fr, fq * 8), boff = lds_byte(wc * 32 + fr, fq * 8);
; __global__ void __launch_bounds__(512, 2) hybrid_fwd(Args args) {
;     ...
;         case ST_GROWS_FFN: case ST_GROWS_SSM: case ST_GROWS_O: { PHSEL(ST_GROWS_FFN);
;             const bf16_t* A0; const bf16_t* B0; int K0; const float* bias = nullptr;
;             if (ty == ST_GROWS_FFN) { A0 = (const bf16_t*)(ws + OFF_ACT); B0 = (const bf16_t*)(ws + OFF_WOUT) + (size_t)arg * D * DFF; K0 = DFF; }
;             else if (ty == ST_GROWS_SSM) { A0 = (const bf16_t*)(ws + OFF_Z); B0 = (const bf16_t*)(ws + OFF_SSMOUT); K0 = DIN; }
;             else { A0 = (const bf16_t*)(ws + OFF_AO); B0 = (const bf16_t*)(ws + OFF_OW); K0 = D; bias = ((const float*)(const GAS float*)args.in[26]); }
; #pragma unroll 1
;             for (int pass = 0; pass < 2; ++pass) {
;                 pg8::Gemm g; pg8::StaticOrder S; float* part = nullptr;
;                 if (pass == 0) { const int pk = c.bid >> 4;
;                     g = pg8::Gemm{A0 + (size_t)TP * K0 + (size_t)pk * 256, B0 + (size_t)pk * 256, TS, D, K0, 256};
;                     S.init_slices(K0 / 256, c.G, c.bid); part = (float*)(ws + OFF_PART) + (size_t)pk * TS * D; }
;                 else { g = pg8::Gemm{A0, B0, TP, D, K0, 0}; S.init(TP, D, c.G, c.bid); }
.LBB0_449:
	v_bfe_i32 v3, v164, 27, 1
	v_lshlrev_b32_e32 v1, 4, v164
	v_lshrrev_b32_e32 v3, 22, v3
	v_add_u32_e32 v3, v1, v3
	v_and_b32_e32 v3, 0xfffffc00, v3
	v_sub_u32_e32 v3, v1, v3
	v_lshrrev_b32_e32 v4, 4, v3
	v_ashrrev_i32_e32 v0, 31, v164
	v_bitop3_b32 v3, v4, v3, 32 bitop3:0x6c
	v_lshrrev_b32_e32 v0, 26, v0
	s_waitcnt lgkmcnt(0)
	v_ashrrev_i32_e32 v5, 31, v3
	v_add_u32_e32 v0, v164, v0
	v_lshrrev_b32_e32 v5, 26, v5
	v_ashrrev_i32_e32 v0, 6, v0
	v_add_u32_e32 v5, v3, v5
	v_lshlrev_b32_e32 v4, 3, v0
	v_ashrrev_i32_e32 v6, 6, v5
	v_and_b32_e32 v5, 0xc0, v5
	v_and_b32_e32 v4, -16, v4
	v_lshlrev_b32_e32 v0, 5, v0
	v_sub_u32_e32 v3, v3, v5
	v_add_u32_e32 v4, v6, v4
	v_and_b32_e32 v0, 32, v0
	v_ashrrev_i16_sdwa v3, v231, sext(v3) dst_sel:DWORD dst_unused:UNUSED_PAD src0_sel:DWORD src1_sel:BYTE_0
	v_add_u32_sdwa v3, v0, sext(v3) dst_sel:DWORD dst_unused:UNUSED_PAD src0_sel:DWORD src1_sel:WORD_0
	v_lshlrev_b32_e32 v0, 1, v4
	v_lshrrev_b32_e32 v5, 2, v4
	v_and_b32_e32 v6, 3, v6
	s_mov_b32 s2, 0x7fffffe0
	v_and_b32_e32 v0, 24, v0
	v_and_b32_e32 v5, 4, v5
	v_and_or_b32 v6, v4, s2, v6
	v_or3_b32 v5, v6, v5, v0
	v_readlane_b32 s6, v254, 15
	s_movk_i32 s98, 0x80
	s_cmpk_eq_u32 s6, 0xb00
	s_cselect_b32 s92, 64, s6
	s_cselect_b32 s98, 0x8000, s98
	s_mov_b32 s99, 0
	s_lshl_b32 s88, s92, 8
	s_lshl_b32 s32, s98, 1
	v_add_u32_e32 v1, 0x2000, v1
	s_add_u32 s10, s90, 0x16608000
	v_mul_lo_u32 v0, s92, v4
	v_mul_lo_u32 v4, s6, v5
	v_add_lshl_u32 v0, v0, v3, 1
	v_add_lshl_u32 v146, v4, v3, 1
	v_ashrrev_i32_e32 v3, 31, v1
	v_lshrrev_b32_e32 v3, 22, v3
	v_add_u32_e32 v3, v1, v3
	v_ashrrev_i32_e32 v3, 10, v3
	v_mul_i32_i24_e32 v4, 0x400, v3
	v_sub_u32_e32 v1, v1, v4
	v_lshrrev_b32_e32 v4, 4, v1
	v_bitop3_b32 v1, v4, v1, 32 bitop3:0x6c
	v_ashrrev_i32_e32 v5, 31, v1
	v_lshrrev_b32_e32 v5, 26, v5
	s_addc_u32 s11, s91, 0
	v_lshlrev_b32_e32 v4, 3, v3
	v_add_u32_e32 v5, v1, v5
	s_add_u32 s12, s90, 0xa14000
	v_and_b32_e32 v4, -16, v4
	v_ashrrev_i32_e32 v6, 6, v5
	s_addc_u32 s13, s91, 0
	v_add_u32_e32 v4, v6, v4
	v_and_b32_e32 v6, 3, v6
	s_lshl_b32 s14, s6, 8
	s_mov_b32 s15, s35
	v_and_or_b32 v6, v4, s2, v6
	s_lshl_b64 s[16:17], s[14:15], 1
	s_lshl_b32 s2, s6, 16
	v_readlane_b32 s4, v254, 18
	v_readlane_b32 s5, v254, 19
	s_add_u32 s2, s4, s2
	v_and_b32_e32 v5, 0xc0, v5
	s_addc_u32 s3, s5, 0
	v_readlane_b32 s4, v253, 29
	v_lshlrev_b32_e32 v3, 5, v3
	v_sub_u32_e32 v1, v1, v5
	v_readlane_b32 s5, v253, 30
	s_cmp_eq_u32 s92, 64
	s_cbranch_scc0 .Lgr_pk_plain
	s_lshl_b64 s[18:19], s[4:5], 8
	s_add_u32 s18, s2, s18
	s_addc_u32 s19, s3, s19
	s_branch .Lgr_pk_done
.Lgr_pk_plain:
	s_add_u32 s18, s2, s4
	s_addc_u32 s19, s3, s5
.Lgr_pk_done:
	v_and_b32_e32 v3, 32, v3
	v_ashrrev_i16_sdwa v1, v231, sext(v1) dst_sel:DWORD dst_unused:UNUSED_PAD src0_sel:DWORD src1_sel:BYTE_0
	v_readlane_b32 s2, v254, 20
	v_add_u32_sdwa v1, v3, sext(v1) dst_sel:DWORD dst_unused:UNUSED_PAD src0_sel:DWORD src1_sel:WORD_0
	v_lshlrev_b32_e32 v3, 1, v4
	v_lshrrev_b32_e32 v5, 2, v4
	v_readlane_b32 s3, v254, 21
	s_add_u32 s20, s2, s4
	v_and_b32_e32 v3, 24, v3
	v_and_b32_e32 v5, 4, v5
	s_addc_u32 s21, s3, s5
	s_lshr_b32 s60, s6, 4
	v_readlane_b32 s2, v251, 34
	v_or3_b32 v3, v6, v5, v3
	v_readlane_b32 s3, v251, 35
	s_add_u32 s2, s90, s2
	v_mul_lo_u32 v4, s92, v4
	v_mul_lo_u32 v3, s6, v3
	s_addc_u32 s3, s91, s3
	v_add_lshl_u32 v166, v4, v1, 1
	v_add_lshl_u32 v168, v3, v1, 1
	v_and_b32_e32 v3, 15, v164
	v_bfe_u32 v4, v164, 4, 2
	v_lshlrev_b32_e32 v5, 2, v164
	s_add_u32 s22, s2, 0x1a808000
	v_lshlrev_b32_e32 v165, 4, v4
	v_lshlrev_b32_e32 v1, 6, v3
	v_and_b32_e32 v5, 32, v5
	s_addc_u32 s23, s3, 0
	v_bitop3_b32 v182, v165, v5, v1 bitop3:0x36
	v_mov_b32_e32 v1, v2
	v_mov_b32_e32 v167, v2
	s_cmp_lg_u64 s[38:39], 0
	v_lshlrev_b32_e32 v153, 3, v4
	v_mov_b32_e32 v147, v2
	v_mov_b32_e32 v169, v2
	v_cmp_eq_u32_e64 s[2:3], 0, v4
	s_cselect_b64 s[24:25], -1, 0
	v_add_u32_e32 v170, s88, v0
	v_add_u32_e32 v172, s88, v166
	v_mov_b32_e32 v171, v2
	v_mov_b32_e32 v173, v2
	s_mov_b64 s[4:5], -1
	s_mov_b64 s[26:27], 0
	s_branch .LBB0_452

; #define PG8_STAGE(bufoff, gbase, voff) do { _Pragma("unroll") for (int _i = 0; _i < 2; ++_i) \
;         __builtin_amdgcn_global_load_lds((const unsigned*)((const char*)(gbase) + (voff)[_i]), (PG8_LAS unsigned*)(lds + (bufoff) + ldsw + _i * 8192), 16, 0, 0); } while (0)
; #define PG8_WAIT_V(n) asm volatile("s_waitcnt vmcnt(" #n ")" ::: "memory")
; #define PG8_BAR __builtin_amdgcn_s_barrier()
; template <class Epi, class Sched, bool ALIGN_EPI = false, bool SP2 = false>
; __device__ __forceinline__ void gemm_phase(PG8_LAS unsigned char* lds, const Gemm g, const Sched& S, const Epi& E, const int tid) {
;     ...
;     const char* cA = (const char*)g.A + (size_t)cur.pm * tstep; const char* cB = (const char*)g.Bt + (size_t)cur.pn * tstep;
;     S.a_ready(cur);
;     if constexpr (SP2) {
;         PG8_STAGE(PG8_SB(0, 0), cB, voffB); PG8_STAGE(PG8_SB(0, 1), cB + hstep, voffB); PG8_STAGE(PG8_SA(0, 0), cA, voffA); PG8_STAGE(PG8_SA(0, 1), cA + hstep, voffA);
;         if (wr == 1) PG8_BAR;
;         PG8_WAIT_V(2); PG8_BAR;
;         PG8_STAGE(PG8_SB(1, 0), cB + kstep, voffB); PG8_STAGE(PG8_SA(1, 0), cA + kstep, voffA); PG8_STAGE(PG8_SB(1, 1), cB + hstep + kstep, voffB);
;         PG8_WAIT_V(6); PG8_BAR;
.LBB0_461:
	s_xor_b64 s[46:47], s[4:5], -1
	s_andn2_b64 vcc, exec, s[6:7]
	s_cbranch_vccnz .LBB0_451
	s_ashr_i32 s6, s77, 31
	s_mul_hi_u32 s7, s16, s77
	s_mul_i32 s6, s16, s6
	s_add_i32 s6, s7, s6
	s_mul_i32 s7, s17, s77
	s_add_i32 s48, s6, s7
	s_ashr_i32 s6, s34, 31
	s_mul_hi_u32 s7, s16, s34
	s_mul_i32 s6, s16, s6
	s_ashr_i32 s5, s50, 6
	s_add_i32 s6, s7, s6
	s_mul_i32 s7, s17, s34
	s_ashr_i32 s4, s50, 8
	s_lshl_b32 s61, s5, 10
	s_add_i32 s6, s6, s7
	s_mul_i32 s7, s16, s34
	s_add_u32 s58, s44, s7
	s_addc_u32 s59, s45, s6
	s_add_i32 s62, s61, 0
	s_add_i32 m0, s62, 0x10000
	s_waitcnt vmcnt(0)
	v_lshl_add_u64 v[8:9], s[58:59], 0, v[146:147]
	global_load_lds_dwordx4 v[8:9], off
	s_add_i32 m0, s62, 0x12000
	s_add_u32 s6, s58, s14
	v_lshl_add_u64 v[10:11], s[58:59], 0, v[168:169]
	s_addc_u32 s7, s59, 0
	global_load_lds_dwordx4 v[10:11], off
	s_add_i32 m0, s62, 0x14000
	s_waitcnt lgkmcnt(0)
	v_lshl_add_u64 v[4:5], s[6:7], 0, v[146:147]
	s_mul_i32 s49, s16, s77
	global_load_lds_dwordx4 v[4:5], off
	s_add_i32 m0, s62, 0x16000
	v_lshl_add_u64 v[6:7], s[6:7], 0, v[168:169]
	s_add_u32 s6, s42, s49
	s_addc_u32 s7, s43, s48
	s_add_i32 s63, s62, 0x2000
	global_load_lds_dwordx4 v[6:7], off
	v_lshl_add_u64 v[14:15], s[6:7], 0, v[0:1]
	s_mov_b32 m0, s62
	s_add_u32 s48, s6, s88
	global_load_lds_dwordx4 v[14:15], off
	v_lshl_add_u64 v[12:13], s[6:7], 0, v[166:167]
	s_mov_b32 m0, s63
	s_addc_u32 s49, s7, 0
	s_add_i32 s64, s62, 0x4000
	global_load_lds_dwordx4 v[12:13], off
	v_lshl_add_u64 v[16:17], s[48:49], 0, v[0:1]
	s_mov_b32 m0, s64
	s_add_i32 s65, s62, 0x6000
	global_load_lds_dwordx4 v[16:17], off
	v_lshl_add_u64 v[16:17], s[48:49], 0, v[166:167]
	s_mov_b32 m0, s65
	s_cmp_eq_u32 s4, 1
	global_load_lds_dwordx4 v[16:17], off
	s_cselect_b64 s[48:49], -1, 0
	s_cmp_lg_u32 s4, 1
	s_cbranch_scc1 .LBB0_464
	s_barrier
.LBB0_464:
	s_add_i32 m0, s62, 0x18000
	v_lshl_add_u64 v[8:9], v[8:9], 0, s[0:1]
	s_waitcnt vmcnt(2)
	s_barrier
	global_load_lds_dwordx4 v[8:9], off
	v_lshl_add_u64 v[8:9], v[10:11], 0, s[0:1]
	s_add_i32 m0, s62, 0x1a000
	s_add_i32 s66, s62, 0x8000
	global_load_lds_dwordx4 v[8:9], off
	v_lshl_add_u64 v[8:9], v[14:15], 0, s[98:99]
	s_mov_b32 m0, s66
	s_add_i32 s67, s62, 0xa000
	global_load_lds_dwordx4 v[8:9], off
	v_lshl_add_u64 v[8:9], v[12:13], 0, s[98:99]
	s_mov_b32 m0, s67
	v_lshl_add_u64 v[4:5], v[4:5], 0, s[0:1]
	global_load_lds_dwordx4 v[8:9], off
	s_add_i32 m0, s62, 0x1c000
	s_lshr_b32 s69, s37, 6
	global_load_lds_dwordx4 v[4:5], off
	v_lshl_add_u64 v[4:5], v[6:7], 0, s[0:1]
	s_add_i32 m0, s62, 0x1e000
	s_and_b32 s68, s5, 3
	global_load_lds_dwordx4 v[4:5], off
	v_lshl_or_b32 v183, s4, 6, v3
	s_lshl_b32 s4, s4, 13
	s_add_i32 s70, s69, -2
	s_cmpk_lt_u32 s50, 0x100
	v_lshlrev_b32_e32 v5, 2, v3
	s_cselect_b64 s[50:51], -1, 0
	s_lshr_b32 s71, s36, 3
	v_lshl_or_b32 v4, v3, 6, v165
	v_and_b32_e32 v5, 32, v5
	s_waitcnt vmcnt(6)
	s_and_b32 s72, s36, 7
	s_add_i32 s73, s71, 1
	v_bitop3_b32 v4, v4, s4, v5 bitop3:0xde
	s_cmp_lg_u64 s[40:41], 0
	v_lshl_or_b32 v184, s68, 12, v182
	v_lshl_or_b32 v185, s68, 5, v153
	s_mov_b32 s37, s35
	s_mov_b32 s74, 0
	s_cselect_b64 s[52:53], -1, 0
	v_add_u32_e32 v186, 0, v4
	s_barrier
	s_branch .LBB0_467

; #define PG8_WAIT_V(n) asm volatile("s_waitcnt vmcnt(" #n ")" ::: "memory")
; #define PG8_BAR __builtin_amdgcn_s_barrier()
; template <class Epi, class Sched, bool ALIGN_EPI = false, bool SP2 = false>
; __device__ __forceinline__ void gemm_phase(PG8_LAS unsigned char* lds, const Gemm g, const Sched& S, const Epi& E, const int tid) {
;     ...
;     for (;;) {
;         const bool has_next = S.next(ui + 1, nxt);
;         const char* nA = has_next ? (const char*)g.A + (size_t)nxt.pm * tstep : cA; const char* nB = has_next ? (const char*)g.Bt + (size_t)nxt.pn * tstep : cB;
;         for (int t = 0; t < nt; t += 2) {
;             const bool last = (t == nt - 2);
;             const char* a1 = cA + (size_t)(t + 1) * kstep;
;             const char* a2 = last ? nA : cA + (size_t)(t + 2) * kstep; const char* b2 = last ? nB : cB + (size_t)(t + 2) * kstep;
;             const char* a3 = a2 + kstep; const char* b3 = b2 + kstep;
;             if (last && has_next) S.a_ready(nxt);
;             if constexpr (SP2) {
;             PG8_LDB(B0, 0, 0); PG8_LDB(B1, 0, 1); PG8_SCHED; PG8_LDA(At, 0, 0); PG8_STAGE(PG8_SA(1, 1), a1 + hstep, voffA);
;             PG8_WAIT_V(8); PG8_WAIT_L(0); PG8_BAR; PG8_MMA(0, 0, At, B0); PG8_MMA(0, 1, At, B1); PG8_BAR; PG8_SCHED;
;             PG8_LDA(At, 0, 1); PG8_STAGE(PG8_SB(0, 0), b2, voffB); PG8_STAGE(PG8_SB(0, 1), b2 + hstep, voffB); PG8_STAGE(PG8_SA(0, 0), a2, voffA);
;             PG8_WAIT_V(8); PG8_WAIT_L(0); PG8_BAR; PG8_MMA(1, 0, At, B0); PG8_MMA(1, 1, At, B1); PG8_BAR; PG8_SCHED;
;             PG8_LDB(B0, 1, 0); PG8_LDB(B1, 1, 1); PG8_SCHED; PG8_LDA(At, 1, 0); PG8_STAGE(PG8_SA(0, 1), a2 + hstep, voffA);
;             PG8_WAIT_V(8); PG8_WAIT_L(0); PG8_BAR; PG8_MMA(0, 0, At, B0); PG8_MMA(0, 1, At, B1); PG8_BAR; PG8_SCHED;
;             PG8_LDA(At, 1, 1); PG8_STAGE(PG8_SB(1, 0), b3, voffB); PG8_STAGE(PG8_SB(1, 1), b3 + hstep, voffB); PG8_STAGE(PG8_SA(1, 0), a3, voffA);
;             PG8_WAIT_V(8); PG8_WAIT_L(0); PG8_BAR; PG8_MMA(1, 0, At, B0); PG8_MMA(1, 1, At, B1); PG8_BAR; PG8_SCHED;
;     ...
; #pragma unroll
;         for (int a = 0; a < 2; ++a)
; #pragma unroll
;             for (int b = 0; b < 2; ++b)
; #pragma unroll
;                 for (int m = 0; m < 4; ++m)
; #pragma unroll
;                     for (int n = 0; n < 2; ++n) acc[a][b][m][n] = (f32x4){0.f, 0.f, 0.f, 0.f};
;         cur = nxt; cA = nA; cB = nB; ++ui;
.LBB0_475:
	s_add_u32 s6, s6, s98
	s_addc_u32 s7, s7, 0
	s_add_u32 s78, s58, 0x100
	v_mov_b32_e32 v4, 0
	s_addc_u32 s79, s59, 0
	s_mov_b32 s58, 0
	v_mov_b32_e32 v5, v4
	v_mov_b32_e32 v6, v4
	v_mov_b32_e32 v7, v4
	v_mov_b32_e32 v8, v4
	v_mov_b32_e32 v9, v4
	v_mov_b32_e32 v10, v4
	v_mov_b32_e32 v11, v4
	v_mov_b32_e32 v20, v4
	v_mov_b32_e32 v21, v4
	v_mov_b32_e32 v22, v4
	v_mov_b32_e32 v23, v4
	v_mov_b32_e32 v24, v4
	v_mov_b32_e32 v25, v4
	v_mov_b32_e32 v26, v4
	v_mov_b32_e32 v27, v4
	v_mov_b32_e32 v36, v4
	v_mov_b32_e32 v37, v4
	v_mov_b32_e32 v38, v4
	v_mov_b32_e32 v39, v4
	v_mov_b32_e32 v40, v4
	v_mov_b32_e32 v41, v4
	v_mov_b32_e32 v42, v4
	v_mov_b32_e32 v43, v4
	v_mov_b32_e32 v52, v4
	v_mov_b32_e32 v53, v4
	v_mov_b32_e32 v54, v4
	v_mov_b32_e32 v55, v4
	v_mov_b32_e32 v56, v4
	v_mov_b32_e32 v57, v4
	v_mov_b32_e32 v58, v4
	v_mov_b32_e32 v59, v4
	v_mov_b32_e32 v12, v4
	v_mov_b32_e32 v13, v4
	v_mov_b32_e32 v14, v4
	v_mov_b32_e32 v15, v4
	v_mov_b32_e32 v16, v4
	v_mov_b32_e32 v17, v4
	v_mov_b32_e32 v18, v4
	v_mov_b32_e32 v19, v4
	v_mov_b32_e32 v28, v4
	v_mov_b32_e32 v29, v4
	v_mov_b32_e32 v30, v4
	v_mov_b32_e32 v31, v4
	v_mov_b32_e32 v32, v4
	v_mov_b32_e32 v33, v4
	v_mov_b32_e32 v34, v4
	v_mov_b32_e32 v35, v4
	v_mov_b32_e32 v44, v4
	v_mov_b32_e32 v45, v4
	v_mov_b32_e32 v46, v4
	v_mov_b32_e32 v47, v4
	v_mov_b32_e32 v48, v4
	v_mov_b32_e32 v49, v4
	v_mov_b32_e32 v50, v4
	v_mov_b32_e32 v51, v4
	v_mov_b32_e32 v60, v4
	v_mov_b32_e32 v61, v4
	v_mov_b32_e32 v62, v4
	v_mov_b32_e32 v63, v4
	v_mov_b32_e32 v64, v4
	v_mov_b32_e32 v65, v4
	v_mov_b32_e32 v66, v4
	v_mov_b32_e32 v67, v4
	v_mov_b32_e32 v68, v4
	v_mov_b32_e32 v69, v4
	v_mov_b32_e32 v70, v4
	v_mov_b32_e32 v71, v4
	v_mov_b32_e32 v72, v4
	v_mov_b32_e32 v73, v4
	v_mov_b32_e32 v74, v4
	v_mov_b32_e32 v75, v4
	v_mov_b32_e32 v84, v4
	v_mov_b32_e32 v85, v4
	v_mov_b32_e32 v86, v4
	v_mov_b32_e32 v87, v4
	v_mov_b32_e32 v88, v4
	v_mov_b32_e32 v89, v4
	v_mov_b32_e32 v90, v4
	v_mov_b32_e32 v91, v4
	v_mov_b32_e32 v100, v4
	v_mov_b32_e32 v101, v4
	v_mov_b32_e32 v102, v4
	v_mov_b32_e32 v103, v4
	v_mov_b32_e32 v104, v4
	v_mov_b32_e32 v105, v4
	v_mov_b32_e32 v106, v4
	v_mov_b32_e32 v107, v4
	v_mov_b32_e32 v116, v4
	v_mov_b32_e32 v117, v4
	v_mov_b32_e32 v118, v4
	v_mov_b32_e32 v119, v4
	v_mov_b32_e32 v120, v4
	v_mov_b32_e32 v121, v4
	v_mov_b32_e32 v122, v4
	v_mov_b32_e32 v123, v4
	v_mov_b32_e32 v76, v4
	v_mov_b32_e32 v77, v4
	v_mov_b32_e32 v78, v4
	v_mov_b32_e32 v79, v4
	v_mov_b32_e32 v80, v4
	v_mov_b32_e32 v81, v4
	v_mov_b32_e32 v82, v4
	v_mov_b32_e32 v83, v4
	v_mov_b32_e32 v92, v4
	v_mov_b32_e32 v93, v4
	v_mov_b32_e32 v94, v4
	v_mov_b32_e32 v95, v4
	v_mov_b32_e32 v96, v4
	v_mov_b32_e32 v97, v4
	v_mov_b32_e32 v98, v4
	v_mov_b32_e32 v99, v4
	v_mov_b32_e32 v108, v4
	v_mov_b32_e32 v109, v4
	v_mov_b32_e32 v110, v4
	v_mov_b32_e32 v111, v4
	v_mov_b32_e32 v112, v4
	v_mov_b32_e32 v113, v4
	v_mov_b32_e32 v114, v4
	v_mov_b32_e32 v115, v4
	v_mov_b32_e32 v124, v4
	v_mov_b32_e32 v125, v4
	v_mov_b32_e32 v126, v4
	v_mov_b32_e32 v127, v4
	v_mov_b32_e32 v128, v4
	v_mov_b32_e32 v129, v4
	v_mov_b32_e32 v130, v4
	v_mov_b32_e32 v131, v4
.LBB0_476:
	s_add_i32 s80, s58, 2
	s_add_u32 s81, s6, s98
	s_addc_u32 s59, s7, 0
	s_add_i32 s87, 0, 0x10000
	s_cmp_eq_u32 s70, s58
	s_cselect_b32 s59, s55, s59
	s_cselect_b32 s58, s54, s81
	v_add_u32_e32 v144, s87, v184
	s_cselect_b32 s83, s57, s79
	s_cselect_b32 s82, s56, s78
	s_add_i32 s81, 0, 0x14000
	ds_read_b128 v[132:135], v144
	ds_read_b128 v[136:139], v144 offset:1024
	ds_read_b128 v[140:143], v144 offset:2048
	ds_read_b128 v[174:177], v144 offset:3072
	v_add_u32_e32 v144, s81, v184
	ds_read_b128 v[178:181], v144
	ds_read_b128 v[188:191], v144 offset:1024
	ds_read_b128 v[192:195], v144 offset:2048
	ds_read_b128 v[196:199], v144 offset:3072
	v_lshl_add_u64 v[144:145], s[6:7], 0, v[170:171]
	s_add_i32 m0, s62, 0xc000
	ds_read_b128 v[200:203], v186
	ds_read_b128 v[204:207], v186 offset:1024
	ds_read_b128 v[208:211], v186 offset:2048
	ds_read_b128 v[212:215], v186 offset:3072
	ds_read_b128 v[216:219], v186 offset:4096
	ds_read_b128 v[220:223], v186 offset:5120
	ds_read_b128 v[224:227], v186 offset:6144
	ds_read_b128 v[238:241], v186 offset:7168
	global_load_lds_dwordx4 v[144:145], off
	v_lshl_add_u64 v[144:145], s[6:7], 0, v[172:173]
	s_add_i32 m0, s62, 0xe000
	s_nop 0
	global_load_lds_dwordx4 v[144:145], off
	s_waitcnt vmcnt(8)
	s_waitcnt lgkmcnt(0)
	s_barrier
	s_setprio 1
	s_waitcnt lgkmcnt(0)
	v_mfma_f32_16x16x32_bf16 v[128:131], v[132:135], v[200:203], v[128:131]
	v_mfma_f32_16x16x32_bf16 v[124:127], v[140:143], v[200:203], v[124:127]
	v_mfma_f32_16x16x32_bf16 v[112:115], v[132:135], v[208:211], v[112:115]
	v_mfma_f32_16x16x32_bf16 v[108:111], v[140:143], v[208:211], v[108:111]
	v_mfma_f32_16x16x32_bf16 v[96:99], v[132:135], v[216:219], v[96:99]
	v_mfma_f32_16x16x32_bf16 v[92:95], v[140:143], v[216:219], v[92:95]
	v_mfma_f32_16x16x32_bf16 v[80:83], v[132:135], v[224:227], v[80:83]
	v_mfma_f32_16x16x32_bf16 v[76:79], v[140:143], v[224:227], v[76:79]
	v_mfma_f32_16x16x32_bf16 v[128:131], v[136:139], v[204:207], v[128:131]
	v_mfma_f32_16x16x32_bf16 v[124:127], v[174:177], v[204:207], v[124:127]
	v_mfma_f32_16x16x32_bf16 v[112:115], v[136:139], v[212:215], v[112:115]
	v_mfma_f32_16x16x32_bf16 v[108:111], v[174:177], v[212:215], v[108:111]
	v_mfma_f32_16x16x32_bf16 v[96:99], v[136:139], v[220:223], v[96:99]
	v_mfma_f32_16x16x32_bf16 v[92:95], v[174:177], v[220:223], v[92:95]
	v_mfma_f32_16x16x32_bf16 v[80:83], v[136:139], v[238:241], v[80:83]
	v_mfma_f32_16x16x32_bf16 v[76:79], v[174:177], v[238:241], v[76:79]
	s_setprio 0
	s_setprio 1
	v_mfma_f32_16x16x32_bf16 v[120:123], v[178:181], v[200:203], v[120:123]
	v_mfma_f32_16x16x32_bf16 v[116:119], v[192:195], v[200:203], v[116:119]
	v_mfma_f32_16x16x32_bf16 v[104:107], v[178:181], v[208:211], v[104:107]
	v_mfma_f32_16x16x32_bf16 v[100:103], v[192:195], v[208:211], v[100:103]
	v_mfma_f32_16x16x32_bf16 v[88:91], v[178:181], v[216:219], v[88:91]
	v_mfma_f32_16x16x32_bf16 v[84:87], v[192:195], v[216:219], v[84:87]
	v_mfma_f32_16x16x32_bf16 v[72:75], v[178:181], v[224:227], v[72:75]
	v_mfma_f32_16x16x32_bf16 v[68:71], v[192:195], v[224:227], v[68:71]
	v_mfma_f32_16x16x32_bf16 v[120:123], v[188:191], v[204:207], v[120:123]
	v_mfma_f32_16x16x32_bf16 v[116:119], v[196:199], v[204:207], v[116:119]
	v_mfma_f32_16x16x32_bf16 v[104:107], v[188:191], v[212:215], v[104:107]
	v_mfma_f32_16x16x32_bf16 v[100:103], v[196:199], v[212:215], v[100:103]
	v_mfma_f32_16x16x32_bf16 v[88:91], v[188:191], v[220:223], v[88:91]
	v_mfma_f32_16x16x32_bf16 v[84:87], v[196:199], v[220:223], v[84:87]
	v_mfma_f32_16x16x32_bf16 v[72:75], v[188:191], v[238:241], v[72:75]
	v_mfma_f32_16x16x32_bf16 v[68:71], v[196:199], v[238:241], v[68:71]
	s_setprio 0
	s_barrier
; #define PG8_STAGE(bufoff, gbase, voff) do { _Pragma("unroll") for (int _i = 0; _i < 2; ++_i) \
;         __builtin_amdgcn_global_load_lds((const unsigned*)((const char*)(gbase) + (voff)[_i]), (PG8_LAS unsigned*)(lds + (bufoff) + ldsw + _i * 8192), 16, 0, 0); } while (0)
; #define PG8_LDA(dst, b, h) do { _Pragma("unroll") for (int m = 0; m < 4; ++m) _Pragma("unroll") for (int k = 0; k < 2; ++k) dst[m][k] = *(const PG8_LAS bf16x8*)(lds + PG8_SA(b, h) + aoff + m * 2048 + k * 1024); } while (0)
; #define PG8_LDB(dst, b, h) do { _Pragma("unroll") for (int n = 0; n < 2; ++n) _Pragma("unroll") for (int k = 0; k < 2; ++k) dst[n][k] = *(const PG8_LAS bf16x8*)(lds + PG8_SB(b, h) + boff + n * 2048 + k * 1024); } while (0)
; #define PG8_MMA(ai, bj, At, Bt) do { __builtin_amdgcn_s_setprio(1); _Pragma("unroll") for (int m = 0; m < 4; ++m) _Pragma("unroll") for (int n = 0; n < 2; ++n) _Pragma("unroll") for (int k = 0; k < 2; ++k) \
;         acc[ai][bj][m][n] = __builtin_amdgcn_mfma_f32_16x16x32_bf16(Bt[n][k], At[m][k], acc[ai][bj][m][n], 0, 0, 0); __builtin_amdgcn_s_setprio(0); } while (0)
; #define PG8_WAIT_V(n) asm volatile("s_waitcnt vmcnt(" #n ")" ::: "memory")
; #define PG8_WAIT_L(n) asm volatile("s_waitcnt lgkmcnt(" #n ")" ::: "memory")
; #define PG8_BAR __builtin_amdgcn_s_barrier()
; #define PG8_SCHED __builtin_amdgcn_sched_barrier(0)
; template <class Epi, class Sched, bool ALIGN_EPI = false, bool SP2 = false>
; __device__ __forceinline__ void gemm_phase(PG8_LAS unsigned char* lds, const Gemm g, const Sched& S, const Epi& E, const int tid) {
;     ...
;             PG8_LDB(B0, 0, 0); PG8_LDB(B1, 0, 1); PG8_SCHED; PG8_LDA(At, 0, 0); PG8_STAGE(PG8_SA(1, 1), a1 + hstep, voffA);
;             PG8_WAIT_V(8); PG8_WAIT_L(0); PG8_BAR; PG8_MMA(0, 0, At, B0); PG8_MMA(0, 1, At, B1); PG8_BAR; PG8_SCHED;
;             PG8_LDA(At, 0, 1); PG8_STAGE(PG8_SB(0, 0), b2, voffB); PG8_STAGE(PG8_SB(0, 1), b2 + hstep, voffB); PG8_STAGE(PG8_SA(0, 0), a2, voffA);
;             PG8_WAIT_V(8); PG8_WAIT_L(0); PG8_BAR; PG8_MMA(1, 0, At, B0); PG8_MMA(1, 1, At, B1); PG8_BAR; PG8_SCHED;
;             PG8_LDB(B0, 1, 0); PG8_LDB(B1, 1, 1); PG8_SCHED; PG8_LDA(At, 1, 0); PG8_STAGE(PG8_SA(0, 1), a2 + hstep, voffA);
;             PG8_WAIT_V(8); PG8_WAIT_L(0); PG8_BAR; PG8_MMA(0, 0, At, B0); PG8_MMA(0, 1, At, B1); PG8_BAR; PG8_SCHED;
	s_add_i32 s87, s87, s61
	v_lshl_add_u64 v[144:145], s[82:83], 0, v[146:147]
	s_mov_b32 m0, s87
	ds_read_b128 v[200:203], v186 offset:16384
	ds_read_b128 v[204:207], v186 offset:17408
	ds_read_b128 v[208:211], v186 offset:18432
	ds_read_b128 v[212:215], v186 offset:19456
	ds_read_b128 v[216:219], v186 offset:20480
	ds_read_b128 v[220:223], v186 offset:21504
	ds_read_b128 v[224:227], v186 offset:22528
	ds_read_b128 v[238:241], v186 offset:23552
	global_load_lds_dwordx4 v[144:145], off
	s_add_i32 m0, s87, 0x2000
	v_lshl_add_u64 v[242:243], s[82:83], 0, v[168:169]
	s_add_u32 s82, s82, s14
	s_addc_u32 s83, s83, 0
	s_add_i32 s81, s81, s61
	global_load_lds_dwordx4 v[242:243], off
	v_lshl_add_u64 v[244:245], s[82:83], 0, v[146:147]
	s_mov_b32 m0, s81
	v_lshl_add_u64 v[246:247], s[82:83], 0, v[168:169]
	global_load_lds_dwordx4 v[244:245], off
	s_add_i32 m0, s81, 0x2000
	v_lshl_add_u64 v[248:249], s[58:59], 0, v[0:1]
	global_load_lds_dwordx4 v[246:247], off
	s_mov_b32 m0, s62
	v_lshl_add_u64 v[148:149], s[58:59], 0, v[166:167]
	global_load_lds_dwordx4 v[248:249], off
	s_mov_b32 m0, s63
	s_nop 0
	global_load_lds_dwordx4 v[148:149], off
	s_waitcnt vmcnt(8)
	s_waitcnt lgkmcnt(0)
	s_barrier
	s_setprio 1
	s_waitcnt lgkmcnt(0)
	v_mfma_f32_16x16x32_bf16 v[64:67], v[132:135], v[200:203], v[64:67]
	v_mfma_f32_16x16x32_bf16 v[60:63], v[140:143], v[200:203], v[60:63]
	v_mfma_f32_16x16x32_bf16 v[48:51], v[132:135], v[208:211], v[48:51]
	v_mfma_f32_16x16x32_bf16 v[44:47], v[140:143], v[208:211], v[44:47]
	v_mfma_f32_16x16x32_bf16 v[32:35], v[132:135], v[216:219], v[32:35]
	v_mfma_f32_16x16x32_bf16 v[28:31], v[140:143], v[216:219], v[28:31]
	v_mfma_f32_16x16x32_bf16 v[16:19], v[132:135], v[224:227], v[16:19]
	v_mfma_f32_16x16x32_bf16 v[12:15], v[140:143], v[224:227], v[12:15]
	v_mfma_f32_16x16x32_bf16 v[64:67], v[136:139], v[204:207], v[64:67]
	v_mfma_f32_16x16x32_bf16 v[60:63], v[174:177], v[204:207], v[60:63]
	v_mfma_f32_16x16x32_bf16 v[48:51], v[136:139], v[212:215], v[48:51]
	v_mfma_f32_16x16x32_bf16 v[44:47], v[174:177], v[212:215], v[44:47]
	v_mfma_f32_16x16x32_bf16 v[32:35], v[136:139], v[220:223], v[32:35]
	v_mfma_f32_16x16x32_bf16 v[28:31], v[174:177], v[220:223], v[28:31]
	v_mfma_f32_16x16x32_bf16 v[16:19], v[136:139], v[238:241], v[16:19]
	v_mfma_f32_16x16x32_bf16 v[12:15], v[174:177], v[238:241], v[12:15]
	s_setprio 0
	s_setprio 1
	v_mfma_f32_16x16x32_bf16 v[56:59], v[178:181], v[200:203], v[56:59]
	v_mfma_f32_16x16x32_bf16 v[52:55], v[192:195], v[200:203], v[52:55]
	v_mfma_f32_16x16x32_bf16 v[40:43], v[178:181], v[208:211], v[40:43]
	v_mfma_f32_16x16x32_bf16 v[36:39], v[192:195], v[208:211], v[36:39]
	v_mfma_f32_16x16x32_bf16 v[24:27], v[178:181], v[216:219], v[24:27]
	v_mfma_f32_16x16x32_bf16 v[20:23], v[192:195], v[216:219], v[20:23]
	v_mfma_f32_16x16x32_bf16 v[8:11], v[178:181], v[224:227], v[8:11]
	v_mfma_f32_16x16x32_bf16 v[4:7], v[192:195], v[224:227], v[4:7]
	v_mfma_f32_16x16x32_bf16 v[56:59], v[188:191], v[204:207], v[56:59]
	v_mfma_f32_16x16x32_bf16 v[52:55], v[196:199], v[204:207], v[52:55]
	v_mfma_f32_16x16x32_bf16 v[40:43], v[188:191], v[212:215], v[40:43]
	v_mfma_f32_16x16x32_bf16 v[36:39], v[196:199], v[212:215], v[36:39]
	v_mfma_f32_16x16x32_bf16 v[24:27], v[188:191], v[220:223], v[24:27]
	v_mfma_f32_16x16x32_bf16 v[20:23], v[196:199], v[220:223], v[20:23]
	v_mfma_f32_16x16x32_bf16 v[8:11], v[188:191], v[238:241], v[8:11]
	v_mfma_f32_16x16x32_bf16 v[4:7], v[196:199], v[238:241], v[4:7]
	s_setprio 0
	s_barrier
	s_add_i32 s81, 0, 0x18000
	v_add_u32_e32 v150, s81, v184
	s_add_i32 s82, 0, 0x1c000
	ds_read_b128 v[132:135], v150
	ds_read_b128 v[136:139], v150 offset:1024
	ds_read_b128 v[140:143], v150 offset:2048
	ds_read_b128 v[174:177], v150 offset:3072
	v_add_u32_e32 v150, s82, v184
	ds_read_b128 v[178:181], v150
	ds_read_b128 v[188:191], v150 offset:1024
	ds_read_b128 v[192:195], v150 offset:2048
	ds_read_b128 v[196:199], v150 offset:3072
	s_add_u32 s58, s58, s88
	s_addc_u32 s59, s59, 0
	s_mov_b32 m0, s64
	v_lshl_add_u64 v[150:151], s[58:59], 0, v[0:1]
	ds_read_b128 v[200:203], v186 offset:32768
	ds_read_b128 v[204:207], v186 offset:33792
	ds_read_b128 v[208:211], v186 offset:34816
	ds_read_b128 v[212:215], v186 offset:35840
	ds_read_b128 v[216:219], v186 offset:36864
	ds_read_b128 v[220:223], v186 offset:37888
	ds_read_b128 v[224:227], v186 offset:38912
	ds_read_b128 v[238:241], v186 offset:39936
	global_load_lds_dwordx4 v[150:151], off
	v_lshl_add_u64 v[150:151], s[58:59], 0, v[166:167]
	s_mov_b32 m0, s65
	s_nop 0
	global_load_lds_dwordx4 v[150:151], off
	s_waitcnt vmcnt(8)
	s_waitcnt lgkmcnt(0)
	s_barrier
; #define PG8_STAGE(bufoff, gbase, voff) do { _Pragma("unroll") for (int _i = 0; _i < 2; ++_i) \
;         __builtin_amdgcn_global_load_lds((const unsigned*)((const char*)(gbase) + (voff)[_i]), (PG8_LAS unsigned*)(lds + (bufoff) + ldsw + _i * 8192), 16, 0, 0); } while (0)
; #define PG8_LDA(dst, b, h) do { _Pragma("unroll") for (int m = 0; m < 4; ++m) _Pragma("unroll") for (int k = 0; k < 2; ++k) dst[m][k] = *(const PG8_LAS bf16x8*)(lds + PG8_SA(b, h) + aoff + m * 2048 + k * 1024); } while (0)
; #define PG8_LDB(dst, b, h) do { _Pragma("unroll") for (int n = 0; n < 2; ++n) _Pragma("unroll") for (int k = 0; k < 2; ++k) dst[n][k] = *(const PG8_LAS bf16x8*)(lds + PG8_SB(b, h) + boff + n * 2048 + k * 1024); } while (0)
; #define PG8_MMA(ai, bj, At, Bt) do { __builtin_amdgcn_s_setprio(1); _Pragma("unroll") for (int m = 0; m < 4; ++m) _Pragma("unroll") for (int n = 0; n < 2; ++n) _Pragma("unroll") for (int k = 0; k < 2; ++k) \
;         acc[ai][bj][m][n] = __builtin_amdgcn_mfma_f32_16x16x32_bf16(Bt[n][k], At[m][k], acc[ai][bj][m][n], 0, 0, 0); __builtin_amdgcn_s_setprio(0); } while (0)
; #define PG8_WAIT_V(n) asm volatile("s_waitcnt vmcnt(" #n ")" ::: "memory")
; #define PG8_WAIT_L(n) asm volatile("s_waitcnt lgkmcnt(" #n ")" ::: "memory")
; #define PG8_BAR __builtin_amdgcn_s_barrier()
; #define PG8_SCHED __builtin_amdgcn_sched_barrier(0)
; template <class Epi, class Sched, bool ALIGN_EPI = false, bool SP2 = false>
; __device__ __forceinline__ void gemm_phase(PG8_LAS unsigned char* lds, const Gemm g, const Sched& S, const Epi& E, const int tid) {
;     ...
;         for (int t = 0; t < nt; t += 2) {
;     ...
;             PG8_WAIT_V(8); PG8_WAIT_L(0); PG8_BAR; PG8_MMA(1, 0, At, B0); PG8_MMA(1, 1, At, B1); PG8_BAR; PG8_SCHED;
;             PG8_LDB(B0, 1, 0); PG8_LDB(B1, 1, 1); PG8_SCHED; PG8_LDA(At, 1, 0); PG8_STAGE(PG8_SA(0, 1), a2 + hstep, voffA);
;             PG8_WAIT_V(8); PG8_WAIT_L(0); PG8_BAR; PG8_MMA(0, 0, At, B0); PG8_MMA(0, 1, At, B1); PG8_BAR; PG8_SCHED;
;             PG8_LDA(At, 1, 1); PG8_STAGE(PG8_SB(1, 0), b3, voffB); PG8_STAGE(PG8_SB(1, 1), b3 + hstep, voffB); PG8_STAGE(PG8_SA(1, 0), a3, voffA);
;             PG8_WAIT_V(8); PG8_WAIT_L(0); PG8_BAR; PG8_MMA(1, 0, At, B0); PG8_MMA(1, 1, At, B1); PG8_BAR; PG8_SCHED;
	s_setprio 1
	s_waitcnt lgkmcnt(0)
	v_mfma_f32_16x16x32_bf16 v[128:131], v[132:135], v[200:203], v[128:131]
	v_mfma_f32_16x16x32_bf16 v[124:127], v[140:143], v[200:203], v[124:127]
	v_mfma_f32_16x16x32_bf16 v[112:115], v[132:135], v[208:211], v[112:115]
	v_mfma_f32_16x16x32_bf16 v[108:111], v[140:143], v[208:211], v[108:111]
	v_mfma_f32_16x16x32_bf16 v[96:99], v[132:135], v[216:219], v[96:99]
	v_mfma_f32_16x16x32_bf16 v[92:95], v[140:143], v[216:219], v[92:95]
	v_mfma_f32_16x16x32_bf16 v[80:83], v[132:135], v[224:227], v[80:83]
	v_mfma_f32_16x16x32_bf16 v[76:79], v[140:143], v[224:227], v[76:79]
	v_mfma_f32_16x16x32_bf16 v[128:131], v[136:139], v[204:207], v[128:131]
	v_mfma_f32_16x16x32_bf16 v[124:127], v[174:177], v[204:207], v[124:127]
	v_mfma_f32_16x16x32_bf16 v[112:115], v[136:139], v[212:215], v[112:115]
	v_mfma_f32_16x16x32_bf16 v[108:111], v[174:177], v[212:215], v[108:111]
	v_mfma_f32_16x16x32_bf16 v[96:99], v[136:139], v[220:223], v[96:99]
	v_mfma_f32_16x16x32_bf16 v[92:95], v[174:177], v[220:223], v[92:95]
	v_mfma_f32_16x16x32_bf16 v[80:83], v[136:139], v[238:241], v[80:83]
	v_mfma_f32_16x16x32_bf16 v[76:79], v[174:177], v[238:241], v[76:79]
	s_setprio 0
	s_setprio 1
	v_mfma_f32_16x16x32_bf16 v[120:123], v[178:181], v[200:203], v[120:123]
	v_mfma_f32_16x16x32_bf16 v[116:119], v[192:195], v[200:203], v[116:119]
	v_mfma_f32_16x16x32_bf16 v[104:107], v[178:181], v[208:211], v[104:107]
	v_mfma_f32_16x16x32_bf16 v[100:103], v[192:195], v[208:211], v[100:103]
	v_mfma_f32_16x16x32_bf16 v[88:91], v[178:181], v[216:219], v[88:91]
	v_mfma_f32_16x16x32_bf16 v[84:87], v[192:195], v[216:219], v[84:87]
	v_mfma_f32_16x16x32_bf16 v[72:75], v[178:181], v[224:227], v[72:75]
	v_mfma_f32_16x16x32_bf16 v[68:71], v[192:195], v[224:227], v[68:71]
	v_mfma_f32_16x16x32_bf16 v[120:123], v[188:191], v[204:207], v[120:123]
	v_mfma_f32_16x16x32_bf16 v[116:119], v[196:199], v[204:207], v[116:119]
	v_mfma_f32_16x16x32_bf16 v[104:107], v[188:191], v[212:215], v[104:107]
	v_mfma_f32_16x16x32_bf16 v[100:103], v[196:199], v[212:215], v[100:103]
	v_mfma_f32_16x16x32_bf16 v[88:91], v[188:191], v[220:223], v[88:91]
	v_mfma_f32_16x16x32_bf16 v[84:87], v[196:199], v[220:223], v[84:87]
	v_mfma_f32_16x16x32_bf16 v[72:75], v[188:191], v[238:241], v[72:75]
	v_mfma_f32_16x16x32_bf16 v[68:71], v[196:199], v[238:241], v[68:71]
	s_setprio 0
	s_barrier
	s_add_i32 s58, s81, s61
	v_lshl_add_u64 v[144:145], v[144:145], 0, s[0:1]
	s_mov_b32 m0, s58
	ds_read_b128 v[200:203], v186 offset:49152
	ds_read_b128 v[204:207], v186 offset:50176
	ds_read_b128 v[208:211], v186 offset:51200
	ds_read_b128 v[212:215], v186 offset:52224
	ds_read_b128 v[216:219], v186 offset:53248
	ds_read_b128 v[220:223], v186 offset:54272
	ds_read_b128 v[224:227], v186 offset:55296
	ds_read_b128 v[238:241], v186 offset:56320
	global_load_lds_dwordx4 v[144:145], off
	v_lshl_add_u64 v[144:145], v[242:243], 0, s[0:1]
	s_add_i32 m0, s58, 0x2000
	s_add_i32 s58, s82, s61
	global_load_lds_dwordx4 v[144:145], off
	v_lshl_add_u64 v[144:145], v[244:245], 0, s[0:1]
	s_mov_b32 m0, s58
	s_nop 0
	global_load_lds_dwordx4 v[144:145], off
	v_lshl_add_u64 v[144:145], v[246:247], 0, s[0:1]
	s_add_i32 m0, s58, 0x2000
	s_nop 0
	global_load_lds_dwordx4 v[144:145], off
	v_lshl_add_u64 v[144:145], v[248:249], 0, s[98:99]
	s_mov_b32 m0, s66
	s_nop 0
	global_load_lds_dwordx4 v[144:145], off
	v_lshl_add_u64 v[144:145], v[148:149], 0, s[98:99]
	s_mov_b32 m0, s67
	s_nop 0
	global_load_lds_dwordx4 v[144:145], off
	s_waitcnt vmcnt(8)
	s_waitcnt lgkmcnt(0)
	s_barrier
	s_setprio 1
	s_waitcnt lgkmcnt(0)
	v_mfma_f32_16x16x32_bf16 v[64:67], v[132:135], v[200:203], v[64:67]
	v_mfma_f32_16x16x32_bf16 v[60:63], v[140:143], v[200:203], v[60:63]
	v_mfma_f32_16x16x32_bf16 v[48:51], v[132:135], v[208:211], v[48:51]
	v_mfma_f32_16x16x32_bf16 v[44:47], v[140:143], v[208:211], v[44:47]
	v_mfma_f32_16x16x32_bf16 v[32:35], v[132:135], v[216:219], v[32:35]
	v_mfma_f32_16x16x32_bf16 v[28:31], v[140:143], v[216:219], v[28:31]
	v_mfma_f32_16x16x32_bf16 v[16:19], v[132:135], v[224:227], v[16:19]
	v_mfma_f32_16x16x32_bf16 v[12:15], v[140:143], v[224:227], v[12:15]
	v_mfma_f32_16x16x32_bf16 v[64:67], v[136:139], v[204:207], v[64:67]
	v_mfma_f32_16x16x32_bf16 v[60:63], v[174:177], v[204:207], v[60:63]
	v_mfma_f32_16x16x32_bf16 v[48:51], v[136:139], v[212:215], v[48:51]
	v_mfma_f32_16x16x32_bf16 v[44:47], v[174:177], v[212:215], v[44:47]
	v_mfma_f32_16x16x32_bf16 v[32:35], v[136:139], v[220:223], v[32:35]
	v_mfma_f32_16x16x32_bf16 v[28:31], v[174:177], v[220:223], v[28:31]
	v_mfma_f32_16x16x32_bf16 v[16:19], v[136:139], v[238:241], v[16:19]
	v_mfma_f32_16x16x32_bf16 v[12:15], v[174:177], v[238:241], v[12:15]
	s_setprio 0
	s_setprio 1
	v_mfma_f32_16x16x32_bf16 v[56:59], v[178:181], v[200:203], v[56:59]
	v_mfma_f32_16x16x32_bf16 v[52:55], v[192:195], v[200:203], v[52:55]
	v_mfma_f32_16x16x32_bf16 v[40:43], v[178:181], v[208:211], v[40:43]
	v_mfma_f32_16x16x32_bf16 v[36:39], v[192:195], v[208:211], v[36:39]
	v_mfma_f32_16x16x32_bf16 v[24:27], v[178:181], v[216:219], v[24:27]
	v_mfma_f32_16x16x32_bf16 v[20:23], v[192:195], v[216:219], v[20:23]
	v_mfma_f32_16x16x32_bf16 v[8:11], v[178:181], v[224:227], v[8:11]
	v_mfma_f32_16x16x32_bf16 v[4:7], v[192:195], v[224:227], v[4:7]
	v_mfma_f32_16x16x32_bf16 v[56:59], v[188:191], v[204:207], v[56:59]
	v_mfma_f32_16x16x32_bf16 v[52:55], v[196:199], v[204:207], v[52:55]
	v_mfma_f32_16x16x32_bf16 v[40:43], v[188:191], v[212:215], v[40:43]
	v_mfma_f32_16x16x32_bf16 v[36:39], v[196:199], v[212:215], v[36:39]
	v_mfma_f32_16x16x32_bf16 v[24:27], v[188:191], v[220:223], v[24:27]
	v_mfma_f32_16x16x32_bf16 v[20:23], v[196:199], v[220:223], v[20:23]
	v_mfma_f32_16x16x32_bf16 v[8:11], v[188:191], v[238:241], v[8:11]
	v_mfma_f32_16x16x32_bf16 v[4:7], v[196:199], v[238:241], v[4:7]
	s_setprio 0
	s_barrier
	s_add_u32 s6, s6, s32
	s_addc_u32 s7, s7, 0
	s_add_u32 s78, s78, 0x100
	s_addc_u32 s79, s79, 0
	s_cmp_ge_u32 s80, s69
	s_mov_b32 s58, s80
	s_cbranch_scc0 .LBB0_476
	s_and_b64 vcc, exec, s[50:51]
	s_cbranch_vccz .LBB0_479
	s_barrier

; __device__ __forceinline__ unsigned cvt_pk_bf16(float lo, float hi) { f32x2 v = {lo, hi}; bf16x2_t b = __builtin_convertvector(v, bf16x2_t); return __builtin_bit_cast(unsigned, b); }
; __device__ __forceinline__ float silu_f(float g) { return g * __builtin_amdgcn_rcpf(1.0f + __expf(-g)); }
;     __device__ __forceinline__ void operator()(const AccT& acc, const pg8::Unit& u, int wr, int wc, int fr, int fq) const {
;         const int row0 = u.pm * 256 + wr * 64 + fr, col0 = u.pn * 128 + wc * 32 + 8 * fq;
; #pragma unroll
;         for (int ai = 0; ai < 2; ++ai)
; #pragma unroll
;             for (int m = 0; m < 4; ++m) {
;                 bf16_t* p = O + (size_t)(row0 + ai * 128 + m * 16) * DFF + col0;
;                 const f32x4 g0 = acc[ai][0][m][0], g1 = acc[ai][0][m][1], u0 = acc[ai][1][m][0], u1 = acc[ai][1][m][1];
;                 u32x4 w;
;                 w.x = cvt_pk_bf16(silu_f(g0[0]) * u0[0], silu_f(g0[1]) * u0[1]); w.y = cvt_pk_bf16(silu_f(g0[2]) * u0[2], silu_f(g0[3]) * u0[3]);
;                 w.z = cvt_pk_bf16(silu_f(g1[0]) * u1[0], silu_f(g1[1]) * u1[1]); w.w = cvt_pk_bf16(silu_f(g1[2]) * u1[2], silu_f(g1[3]) * u1[3]);
;                 *(u32x4*)p = w;
;             }
;     }
.LBB0_525:
	s_mov_b32 s68, 0xbfb8aa3b
	s_mov_b32 s69, 0xbfb8aa3b
	s_mov_b32 s70, 1.0
	s_mov_b32 s71, 1.0
	s_andn2_b64 vcc, exec, s[2:3]
	s_mul_i32 s72, s46, 44
	s_lshl_b32 s73, s45, 1
	s_add_i32 s72, s72, s73
	s_lshl_b32 s72, s72, 15
	s_add_u32 s74, s4, s72
	s_addc_u32 s75, s5, 0
	v_lshrrev_b32_e32 v170, 6, v147
	v_and_b32_e32 v171, 63, v147
	v_lshlrev_b32_e32 v170, 15, v170
	v_lshl_add_u32 v170, v171, 1, v170
	v_lshl_add_u32 v170, v3, 7, v170
	v_mov_b32_e32 v171, 0
	v_lshl_add_u64 v[172:173], s[74:75], 0, v[170:171]
	s_mov_b64 s[76:77], 0x1000
	v_lshl_add_u64 v[174:175], v[172:173], 0, s[76:77]
	s_mov_b64 s[76:77], 0x4000
	v_lshl_add_u64 v[176:177], v[172:173], 0, s[76:77]
	s_mov_b64 s[76:77], 0x5000
	v_lshl_add_u64 v[178:179], v[172:173], 0, s[76:77]
	v_pk_mul_f32 v[180:181], v[128:129], s[68:69]
	v_pk_mul_f32 v[182:183], v[130:131], s[68:69]
	v_pk_mul_f32 v[184:185], v[120:121], s[68:69]
	v_pk_mul_f32 v[186:187], v[122:123], s[68:69]
	v_exp_f32_e32 v180, v180
	v_exp_f32_e32 v181, v181
	v_exp_f32_e32 v182, v182
	v_exp_f32_e32 v183, v183
	v_exp_f32_e32 v184, v184
	v_exp_f32_e32 v185, v185
	v_exp_f32_e32 v186, v186
	v_exp_f32_e32 v187, v187
	v_pk_add_f32 v[180:181], v[180:181], s[70:71]
	v_pk_add_f32 v[182:183], v[182:183], s[70:71]
	v_pk_add_f32 v[184:185], v[184:185], s[70:71]
	v_pk_add_f32 v[186:187], v[186:187], s[70:71]
	v_rcp_f32_e32 v180, v180
	v_rcp_f32_e32 v181, v181
	v_rcp_f32_e32 v182, v182
	v_rcp_f32_e32 v183, v183
	v_rcp_f32_e32 v184, v184
	v_rcp_f32_e32 v185, v185
	v_rcp_f32_e32 v186, v186
	v_rcp_f32_e32 v187, v187
	v_pk_mul_f32 v[180:181], v[128:129], v[180:181]
	v_pk_mul_f32 v[182:183], v[130:131], v[182:183]
	v_pk_mul_f32 v[184:185], v[120:121], v[184:185]
	v_pk_mul_f32 v[186:187], v[122:123], v[186:187]
	v_pk_mul_f32 v[180:181], v[180:181], v[124:125]
	v_pk_mul_f32 v[182:183], v[182:183], v[126:127]
	v_pk_mul_f32 v[184:185], v[184:185], v[116:117]
	v_pk_mul_f32 v[186:187], v[186:187], v[118:119]
	v_cvt_pk_bf16_f32 v188, v180, v181
	v_cvt_pk_bf16_f32 v189, v182, v183
	v_cvt_pk_bf16_f32 v190, v184, v185
	v_cvt_pk_bf16_f32 v191, v186, v187
	global_store_dwordx4 v[172:173], v[188:191], off
	v_pk_mul_f32 v[180:181], v[112:113], s[68:69]
	v_pk_mul_f32 v[182:183], v[114:115], s[68:69]
	v_pk_mul_f32 v[184:185], v[104:105], s[68:69]
	v_pk_mul_f32 v[186:187], v[106:107], s[68:69]
	v_exp_f32_e32 v180, v180
	v_exp_f32_e32 v181, v181
	v_exp_f32_e32 v182, v182
	v_exp_f32_e32 v183, v183
	v_exp_f32_e32 v184, v184
	v_exp_f32_e32 v185, v185
	v_exp_f32_e32 v186, v186
	v_exp_f32_e32 v187, v187
	v_pk_add_f32 v[180:181], v[180:181], s[70:71]
	v_pk_add_f32 v[182:183], v[182:183], s[70:71]
	v_pk_add_f32 v[184:185], v[184:185], s[70:71]
	v_pk_add_f32 v[186:187], v[186:187], s[70:71]
	v_rcp_f32_e32 v180, v180
	v_rcp_f32_e32 v181, v181
	v_rcp_f32_e32 v182, v182
	v_rcp_f32_e32 v183, v183
	v_rcp_f32_e32 v184, v184
	v_rcp_f32_e32 v185, v185
	v_rcp_f32_e32 v186, v186
	v_rcp_f32_e32 v187, v187
	v_pk_mul_f32 v[180:181], v[112:113], v[180:181]
	v_pk_mul_f32 v[182:183], v[114:115], v[182:183]
	v_pk_mul_f32 v[184:185], v[104:105], v[184:185]
	v_pk_mul_f32 v[186:187], v[106:107], v[186:187]
	v_pk_mul_f32 v[180:181], v[180:181], v[108:109]
	v_pk_mul_f32 v[182:183], v[182:183], v[110:111]
	v_pk_mul_f32 v[184:185], v[184:185], v[100:101]
	v_pk_mul_f32 v[186:187], v[186:187], v[102:103]
	v_cvt_pk_bf16_f32 v192, v180, v181
	v_cvt_pk_bf16_f32 v193, v182, v183
	v_cvt_pk_bf16_f32 v194, v184, v185
	v_cvt_pk_bf16_f32 v195, v186, v187
	global_store_dwordx4 v[172:173], v[192:195], off offset:2048
	v_pk_mul_f32 v[180:181], v[96:97], s[68:69]
	v_pk_mul_f32 v[182:183], v[98:99], s[68:69]
	v_pk_mul_f32 v[184:185], v[88:89], s[68:69]
	v_pk_mul_f32 v[186:187], v[90:91], s[68:69]
	v_exp_f32_e32 v180, v180
	v_exp_f32_e32 v181, v181
	v_exp_f32_e32 v182, v182
	v_exp_f32_e32 v183, v183
	v_exp_f32_e32 v184, v184
	v_exp_f32_e32 v185, v185
	v_exp_f32_e32 v186, v186
	v_exp_f32_e32 v187, v187
	v_pk_add_f32 v[180:181], v[180:181], s[70:71]
	v_pk_add_f32 v[182:183], v[182:183], s[70:71]
	v_pk_add_f32 v[184:185], v[184:185], s[70:71]
	v_pk_add_f32 v[186:187], v[186:187], s[70:71]
	v_rcp_f32_e32 v180, v180
	v_rcp_f32_e32 v181, v181
	v_rcp_f32_e32 v182, v182
	v_rcp_f32_e32 v183, v183
	v_rcp_f32_e32 v184, v184
	v_rcp_f32_e32 v185, v185
	v_rcp_f32_e32 v186, v186
	v_rcp_f32_e32 v187, v187
	v_pk_mul_f32 v[180:181], v[96:97], v[180:181]
	v_pk_mul_f32 v[182:183], v[98:99], v[182:183]
	v_pk_mul_f32 v[184:185], v[88:89], v[184:185]
	v_pk_mul_f32 v[186:187], v[90:91], v[186:187]
	v_pk_mul_f32 v[180:181], v[180:181], v[92:93]
	v_pk_mul_f32 v[182:183], v[182:183], v[94:95]
	v_pk_mul_f32 v[184:185], v[184:185], v[84:85]
	v_pk_mul_f32 v[186:187], v[186:187], v[86:87]
	v_cvt_pk_bf16_f32 v188, v180, v181
	v_cvt_pk_bf16_f32 v189, v182, v183
	v_cvt_pk_bf16_f32 v190, v184, v185
	v_cvt_pk_bf16_f32 v191, v186, v187
	global_store_dwordx4 v[174:175], v[188:191], off
	v_pk_mul_f32 v[180:181], v[80:81], s[68:69]
	v_pk_mul_f32 v[182:183], v[82:83], s[68:69]
	v_pk_mul_f32 v[184:185], v[72:73], s[68:69]
	v_pk_mul_f32 v[186:187], v[74:75], s[68:69]
	v_exp_f32_e32 v180, v180
	v_exp_f32_e32 v181, v181
	v_exp_f32_e32 v182, v182
	v_exp_f32_e32 v183, v183
	v_exp_f32_e32 v184, v184
	v_exp_f32_e32 v185, v185
	v_exp_f32_e32 v186, v186
	v_exp_f32_e32 v187, v187
	v_pk_add_f32 v[180:181], v[180:181], s[70:71]
	v_pk_add_f32 v[182:183], v[182:183], s[70:71]
	v_pk_add_f32 v[184:185], v[184:185], s[70:71]
	v_pk_add_f32 v[186:187], v[186:187], s[70:71]
	v_rcp_f32_e32 v180, v180
	v_rcp_f32_e32 v181, v181
	v_rcp_f32_e32 v182, v182
	v_rcp_f32_e32 v183, v183
	v_rcp_f32_e32 v184, v184
	v_rcp_f32_e32 v185, v185
	v_rcp_f32_e32 v186, v186
; __device__ __forceinline__ unsigned cvt_pk_bf16(float lo, float hi) { f32x2 v = {lo, hi}; bf16x2_t b = __builtin_convertvector(v, bf16x2_t); return __builtin_bit_cast(unsigned, b); }
; __device__ __forceinline__ float silu_f(float g) { return g * __builtin_amdgcn_rcpf(1.0f + __expf(-g)); }
;     __device__ __forceinline__ void operator()(const AccT& acc, const pg8::Unit& u, int wr, int wc, int fr, int fq) const {
;         const int row0 = u.pm * 256 + wr * 64 + fr, col0 = u.pn * 128 + wc * 32 + 8 * fq;
; #pragma unroll
;         for (int ai = 0; ai < 2; ++ai)
; #pragma unroll
;             for (int m = 0; m < 4; ++m) {
;                 bf16_t* p = O + (size_t)(row0 + ai * 128 + m * 16) * DFF + col0;
;                 const f32x4 g0 = acc[ai][0][m][0], g1 = acc[ai][0][m][1], u0 = acc[ai][1][m][0], u1 = acc[ai][1][m][1];
;                 u32x4 w;
;                 w.x = cvt_pk_bf16(silu_f(g0[0]) * u0[0], silu_f(g0[1]) * u0[1]); w.y = cvt_pk_bf16(silu_f(g0[2]) * u0[2], silu_f(g0[3]) * u0[3]);
;                 w.z = cvt_pk_bf16(silu_f(g1[0]) * u1[0], silu_f(g1[1]) * u1[1]); w.w = cvt_pk_bf16(silu_f(g1[2]) * u1[2], silu_f(g1[3]) * u1[3]);
;                 *(u32x4*)p = w;
;             }
;     }
	v_rcp_f32_e32 v187, v187
	v_pk_mul_f32 v[180:181], v[80:81], v[180:181]
	v_pk_mul_f32 v[182:183], v[82:83], v[182:183]
	v_pk_mul_f32 v[184:185], v[72:73], v[184:185]
	v_pk_mul_f32 v[186:187], v[74:75], v[186:187]
	v_pk_mul_f32 v[180:181], v[180:181], v[76:77]
	v_pk_mul_f32 v[182:183], v[182:183], v[78:79]
	v_pk_mul_f32 v[184:185], v[184:185], v[68:69]
	v_pk_mul_f32 v[186:187], v[186:187], v[70:71]
	v_cvt_pk_bf16_f32 v192, v180, v181
	v_cvt_pk_bf16_f32 v193, v182, v183
	v_cvt_pk_bf16_f32 v194, v184, v185
	v_cvt_pk_bf16_f32 v195, v186, v187
	global_store_dwordx4 v[174:175], v[192:195], off offset:2048
	v_pk_mul_f32 v[180:181], v[64:65], s[68:69]
	v_pk_mul_f32 v[182:183], v[66:67], s[68:69]
	v_pk_mul_f32 v[184:185], v[56:57], s[68:69]
	v_pk_mul_f32 v[186:187], v[58:59], s[68:69]
	v_exp_f32_e32 v180, v180
	v_exp_f32_e32 v181, v181
	v_exp_f32_e32 v182, v182
	v_exp_f32_e32 v183, v183
	v_exp_f32_e32 v184, v184
	v_exp_f32_e32 v185, v185
	v_exp_f32_e32 v186, v186
	v_exp_f32_e32 v187, v187
	v_pk_add_f32 v[180:181], v[180:181], s[70:71]
	v_pk_add_f32 v[182:183], v[182:183], s[70:71]
	v_pk_add_f32 v[184:185], v[184:185], s[70:71]
	v_pk_add_f32 v[186:187], v[186:187], s[70:71]
	v_rcp_f32_e32 v180, v180
	v_rcp_f32_e32 v181, v181
	v_rcp_f32_e32 v182, v182
	v_rcp_f32_e32 v183, v183
	v_rcp_f32_e32 v184, v184
	v_rcp_f32_e32 v185, v185
	v_rcp_f32_e32 v186, v186
	v_rcp_f32_e32 v187, v187
	v_pk_mul_f32 v[180:181], v[64:65], v[180:181]
	v_pk_mul_f32 v[182:183], v[66:67], v[182:183]
	v_pk_mul_f32 v[184:185], v[56:57], v[184:185]
	v_pk_mul_f32 v[186:187], v[58:59], v[186:187]
	v_pk_mul_f32 v[180:181], v[180:181], v[60:61]
	v_pk_mul_f32 v[182:183], v[182:183], v[62:63]
	v_pk_mul_f32 v[184:185], v[184:185], v[52:53]
	v_pk_mul_f32 v[186:187], v[186:187], v[54:55]
	v_cvt_pk_bf16_f32 v188, v180, v181
	v_cvt_pk_bf16_f32 v189, v182, v183
	v_cvt_pk_bf16_f32 v190, v184, v185
	v_cvt_pk_bf16_f32 v191, v186, v187
	global_store_dwordx4 v[176:177], v[188:191], off
	v_pk_mul_f32 v[180:181], v[48:49], s[68:69]
	v_pk_mul_f32 v[182:183], v[50:51], s[68:69]
	v_pk_mul_f32 v[184:185], v[40:41], s[68:69]
	v_pk_mul_f32 v[186:187], v[42:43], s[68:69]
	v_exp_f32_e32 v180, v180
	v_exp_f32_e32 v181, v181
	v_exp_f32_e32 v182, v182
	v_exp_f32_e32 v183, v183
	v_exp_f32_e32 v184, v184
	v_exp_f32_e32 v185, v185
	v_exp_f32_e32 v186, v186
	v_exp_f32_e32 v187, v187
	v_pk_add_f32 v[180:181], v[180:181], s[70:71]
	v_pk_add_f32 v[182:183], v[182:183], s[70:71]
	v_pk_add_f32 v[184:185], v[184:185], s[70:71]
	v_pk_add_f32 v[186:187], v[186:187], s[70:71]
	v_rcp_f32_e32 v180, v180
	v_rcp_f32_e32 v181, v181
	v_rcp_f32_e32 v182, v182
	v_rcp_f32_e32 v183, v183
	v_rcp_f32_e32 v184, v184
	v_rcp_f32_e32 v185, v185
	v_rcp_f32_e32 v186, v186
	v_rcp_f32_e32 v187, v187
	v_pk_mul_f32 v[180:181], v[48:49], v[180:181]
	v_pk_mul_f32 v[182:183], v[50:51], v[182:183]
	v_pk_mul_f32 v[184:185], v[40:41], v[184:185]
	v_pk_mul_f32 v[186:187], v[42:43], v[186:187]
	v_pk_mul_f32 v[180:181], v[180:181], v[44:45]
	v_pk_mul_f32 v[182:183], v[182:183], v[46:47]
	v_pk_mul_f32 v[184:185], v[184:185], v[36:37]
	v_pk_mul_f32 v[186:187], v[186:187], v[38:39]
	v_cvt_pk_bf16_f32 v192, v180, v181
	v_cvt_pk_bf16_f32 v193, v182, v183
	v_cvt_pk_bf16_f32 v194, v184, v185
	v_cvt_pk_bf16_f32 v195, v186, v187
	global_store_dwordx4 v[176:177], v[192:195], off offset:2048
	v_pk_mul_f32 v[180:181], v[32:33], s[68:69]
	v_pk_mul_f32 v[182:183], v[34:35], s[68:69]
	v_pk_mul_f32 v[184:185], v[24:25], s[68:69]
	v_pk_mul_f32 v[186:187], v[26:27], s[68:69]
	v_exp_f32_e32 v180, v180
	v_exp_f32_e32 v181, v181
	v_exp_f32_e32 v182, v182
	v_exp_f32_e32 v183, v183
	v_exp_f32_e32 v184, v184
	v_exp_f32_e32 v185, v185
	v_exp_f32_e32 v186, v186
	v_exp_f32_e32 v187, v187
	v_pk_add_f32 v[180:181], v[180:181], s[70:71]
	v_pk_add_f32 v[182:183], v[182:183], s[70:71]
	v_pk_add_f32 v[184:185], v[184:185], s[70:71]
	v_pk_add_f32 v[186:187], v[186:187], s[70:71]
	v_rcp_f32_e32 v180, v180
	v_rcp_f32_e32 v181, v181
	v_rcp_f32_e32 v182, v182
	v_rcp_f32_e32 v183, v183
	v_rcp_f32_e32 v184, v184
	v_rcp_f32_e32 v185, v185
	v_rcp_f32_e32 v186, v186
	v_rcp_f32_e32 v187, v187
	v_pk_mul_f32 v[180:181], v[32:33], v[180:181]
	v_pk_mul_f32 v[182:183], v[34:35], v[182:183]
	v_pk_mul_f32 v[184:185], v[24:25], v[184:185]
	v_pk_mul_f32 v[186:187], v[26:27], v[186:187]
	v_pk_mul_f32 v[180:181], v[180:181], v[28:29]
	v_pk_mul_f32 v[182:183], v[182:183], v[30:31]
	v_pk_mul_f32 v[184:185], v[184:185], v[20:21]
	v_pk_mul_f32 v[186:187], v[186:187], v[22:23]
	v_cvt_pk_bf16_f32 v188, v180, v181
	v_cvt_pk_bf16_f32 v189, v182, v183
	v_cvt_pk_bf16_f32 v190, v184, v185
	v_cvt_pk_bf16_f32 v191, v186, v187
	global_store_dwordx4 v[178:179], v[188:191], off
	v_pk_mul_f32 v[180:181], v[16:17], s[68:69]
	v_pk_mul_f32 v[182:183], v[18:19], s[68:69]
	v_pk_mul_f32 v[184:185], v[8:9], s[68:69]
	v_pk_mul_f32 v[186:187], v[10:11], s[68:69]
	v_exp_f32_e32 v180, v180
	v_exp_f32_e32 v181, v181
	v_exp_f32_e32 v182, v182
	v_exp_f32_e32 v183, v183
	v_exp_f32_e32 v184, v184
	v_exp_f32_e32 v185, v185
	v_exp_f32_e32 v186, v186
	v_exp_f32_e32 v187, v187
	v_pk_add_f32 v[180:181], v[180:181], s[70:71]
	v_pk_add_f32 v[182:183], v[182:183], s[70:71]
	v_pk_add_f32 v[184:185], v[184:185], s[70:71]
	v_pk_add_f32 v[186:187], v[186:187], s[70:71]
	v_rcp_f32_e32 v180, v180
	v_rcp_f32_e32 v181, v181
	v_rcp_f32_e32 v182, v182
	v_rcp_f32_e32 v183, v183
	v_rcp_f32_e32 v184, v184
	v_rcp_f32_e32 v185, v185
	v_rcp_f32_e32 v186, v186
	v_rcp_f32_e32 v187, v187
	v_pk_mul_f32 v[180:181], v[16:17], v[180:181]
	v_pk_mul_f32 v[182:183], v[18:19], v[182:183]
	v_pk_mul_f32 v[184:185], v[8:9], v[184:185]
	v_pk_mul_f32 v[186:187], v[10:11], v[186:187]
	v_pk_mul_f32 v[180:181], v[180:181], v[12:13]
	v_pk_mul_f32 v[182:183], v[182:183], v[14:15]
	v_pk_mul_f32 v[184:185], v[184:185], v[4:5]
	v_pk_mul_f32 v[186:187], v[186:187], v[6:7]
	v_cvt_pk_bf16_f32 v192, v180, v181
	v_cvt_pk_bf16_f32 v193, v182, v183
	v_cvt_pk_bf16_f32 v194, v184, v185
	v_cvt_pk_bf16_f32 v195, v186, v187
	global_store_dwordx4 v[178:179], v[192:195], off offset:2048
	s_mov_b64 s[18:19], -1
	s_cbranch_vccnz .LBB0_518
	s_andn2_b64 vcc, exec, s[6:7]
	s_cbranch_vccnz .LBB0_517
	s_barrier
	s_branch .LBB0_517
